# v29 plus: input-projection K-loop uses one static priority raise for waves 4-7 instead of per-phase s_setprio flips
# baseline (speedup 1.0000x reference)
; #define PG8_STAGE(bufoff, gbase, voff) do { _Pragma("unroll") for (int _i = 0; _i < 2; ++_i) \
;         __builtin_amdgcn_global_load_lds((const unsigned*)((const char*)(gbase) + (voff)[_i]), (LAS unsigned*)(lds + (bufoff) + ldsw + _i * 8192), 16, 0, 0); } while (0)
; #define PG8_BAR __builtin_amdgcn_s_barrier()
; template <class Epi, class Sched>
; __device__ __forceinline__ void gemm_phase(LAS unsigned char* lds, const Gemm g, const Sched& S, const Epi& E) {
;     const int tid = threadIdx.x, wid = __builtin_amdgcn_readfirstlane(tid >> 6), lane = tid & 63, wr = wid >> 2, wc = wid & 3, fr = lane & 15, fq = lane >> 4;
;     const int K = g.K, nt = K / BK;
;     unsigned voffA[2], voffB[2];
; #pragma unroll
;     for (int i = 0; i < 2; ++i) { int R, C; stage_rc(tid * 16 + i * 8192, R, C); voffA[i] = (unsigned)(R * g.lda + C) * 2u; voffB[i] = (unsigned)(R * g.ldb + C) * 2u; }
;     const size_t kstep = (size_t)(BK * 2);
;     const size_t hstepA = (size_t)HALF * g.lda * 2, hstepB = (size_t)HALF * g.ldb * 2;
;     const size_t tstepA = 2 * hstepA, tstepB = 2 * hstepB;
;     const unsigned ldsw = (unsigned)wid * 1024u;
;     const int aoff = lds_byte(wr * 64 + fr, fq * 8), boff = lds_byte(wc * 32 + fr, fq * 8);
;     ...
;     Unit cur, nxt; int ui = 0;
;     if (!S.next(0, cur)) return;
;     f32x4 acc[2][2][4][2];
; #pragma unroll
;     for (int a = 0; a < 2; ++a)
; #pragma unroll
;         for (int b = 0; b < 2; ++b)
; #pragma unroll
;             for (int m = 0; m < 4; ++m)
; #pragma unroll
;                 for (int n = 0; n < 2; ++n) acc[a][b][m][n] = (f32x4){0.f, 0.f, 0.f, 0.f};
;     bf16x8 At[4][2], B0[2][2], B1[2][2];
;     const char* cA = (const char*)g.A + (size_t)cur.pm * tstepA; const char* cB = (const char*)g.Bt + (size_t)cur.pn * tstepB;
;     PG8_STAGE(PG8_SB(0, 0), cB, voffB); PG8_STAGE(PG8_SB(0, 1), cB + hstepB, voffB); PG8_STAGE(PG8_SA(0, 0), cA, voffA); PG8_STAGE(PG8_SA(0, 1), cA + hstepA, voffA);
;     if (wr == 1) PG8_BAR;
.LBB0_108:
	s_andn2_b64 vcc, exec, s[0:1]
	s_cbranch_vccnz .LBB0_242
	v_lshlrev_b32_e32 v0, 4, v193
	v_and_b32_e32 v1, 32, v193
	v_bfe_u32 v10, v193, 2, 4
	v_lshrrev_b32_e32 v2, 3, v193
	s_movk_i32 s0, 0x70
	v_add_u32_e32 v11, 0x2000, v0
	s_lshr_b32 s7, s10, 6
	v_bitop3_b32 v8, v0, v1, 48 bitop3:0x6c
	v_and_or_b32 v2, v2, s0, v10
	v_lshrrev_b32_e32 v0, 7, v11
	s_movk_i32 s0, 0xf0
	s_waitcnt lgkmcnt(0)
	s_ashr_i32 s79, s78, 31
	s_ashr_i32 s77, s76, 31
	v_and_or_b32 v0, v0, s0, v10
	s_lshr_b32 s11, s10, 8
	s_lshl_b32 s33, s7, 10
	s_lshl_b64 s[0:1], s[78:79], 19
	s_lshl_b64 s[4:5], s[76:77], 19
	v_and_b32_e32 v9, 64, v193
	s_add_u32 s4, s8, s4
	v_or_b32_e32 v1, v8, v9
	s_addc_u32 s5, s9, s5
	s_add_i32 s45, s33, 0
	v_lshl_or_b32 v152, v2, 11, v1
	s_add_i32 m0, s45, 0x10000
	v_writelane_b32 v255, s14, 6
	global_load_lds_dwordx4 v152, s[4:5]
	s_add_i32 m0, s45, 0x12000
	v_writelane_b32 v255, s15, 7
	v_lshl_or_b32 v154, v0, 11, v1
	s_add_u32 s12, s4, 0x40000
	v_writelane_b32 v255, s80, 8
	global_load_lds_dwordx4 v154, s[4:5]
	s_addc_u32 s13, s5, 0
	s_add_i32 m0, s45, 0x14000
	v_writelane_b32 v255, s84, 9
	global_load_lds_dwordx4 v152, s[12:13]
	s_add_i32 m0, s45, 0x16000
	v_writelane_b32 v255, s85, 10
	s_add_u32 s0, s62, s0
	v_writelane_b32 v255, s81, 11
	s_addc_u32 s1, s63, s1
	s_add_i32 s77, s45, 0x2000
	v_writelane_b32 v255, s82, 12
	global_load_lds_dwordx4 v154, s[12:13]
	s_mov_b32 m0, s45
	s_add_u32 s12, s0, 0x40000
	v_writelane_b32 v255, s83, 13
	global_load_lds_dwordx4 v152, s[0:1]
	s_mov_b32 m0, s77
	s_addc_u32 s13, s1, 0
	s_add_i32 s82, s45, 0x4000
	global_load_lds_dwordx4 v154, s[0:1]
	s_mov_b32 m0, s82
	s_add_i32 s83, s45, 0x6000
	global_load_lds_dwordx4 v152, s[12:13]
	s_mov_b32 m0, s83
	v_mov_b32_e32 v157, 0
	global_load_lds_dwordx4 v154, s[12:13]
	v_mov_b32_e32 v153, v157
	v_mov_b32_e32 v155, v157
	s_cmp_eq_u32 s11, 1
	s_mov_b32 s19, 0
	v_lshl_add_u64 v[6:7], s[4:5], 0, v[152:153]
	v_lshl_add_u64 v[4:5], s[4:5], 0, v[154:155]
	s_mov_b64 s[30:31], 0x40000
	v_lshl_add_u64 v[0:1], s[0:1], 0, v[152:153]
	s_cselect_b64 s[16:17], -1, 0
	s_cmp_lg_u32 s11, 1
	v_lshl_add_u64 v[2:3], s[0:1], 0, v[154:155]
	s_cbranch_scc1 .LBB0_111
	s_barrier
	s_setprio 1

; #define PG8_STAGE(bufoff, gbase, voff) do { _Pragma("unroll") for (int _i = 0; _i < 2; ++_i) \
;         __builtin_amdgcn_global_load_lds((const unsigned*)((const char*)(gbase) + (voff)[_i]), (LAS unsigned*)(lds + (bufoff) + ldsw + _i * 8192), 16, 0, 0); } while (0)
; #define PG8_LDA(dst, b, h) do { _Pragma("unroll") for (int m = 0; m < 4; ++m) _Pragma("unroll") for (int k = 0; k < 2; ++k) dst[m][k] = *(const LAS bf16x8*)(lds + PG8_SA(b, h) + aoff + m * 2048 + k * 1024); } while (0)
; #define PG8_LDB(dst, b, h) do { _Pragma("unroll") for (int n = 0; n < 2; ++n) _Pragma("unroll") for (int k = 0; k < 2; ++k) dst[n][k] = *(const LAS bf16x8*)(lds + PG8_SB(b, h) + boff + n * 2048 + k * 1024); } while (0)
; #define PG8_MMA(ai, bj, At, Bt) do { __builtin_amdgcn_s_setprio(1); _Pragma("unroll") for (int m = 0; m < 4; ++m) _Pragma("unroll") for (int n = 0; n < 2; ++n) _Pragma("unroll") for (int k = 0; k < 2; ++k) \
;         acc[ai][bj][m][n] = __builtin_amdgcn_mfma_f32_16x16x32_bf16(Bt[n][k], At[m][k], acc[ai][bj][m][n], 0, 0, 0); __builtin_amdgcn_s_setprio(0); } while (0)
; #define PG8_WAIT_V(n) asm volatile("s_waitcnt vmcnt(" #n ")" ::: "memory")
; #define PG8_WAIT_L(n) asm volatile("s_waitcnt lgkmcnt(" #n ")" ::: "memory")
; #define PG8_BAR __builtin_amdgcn_s_barrier()
; #define PG8_SCHED __builtin_amdgcn_sched_barrier(0)
; template <class Epi, class Sched>
; __device__ __forceinline__ void gemm_phase(LAS unsigned char* lds, const Gemm g, const Sched& S, const Epi& E) {
;     ...
;             const bool last = (t == nt - 2);
;             const char* a1 = cA + (size_t)(t + 1) * kstep;
;             const char* a2 = last ? nA : cA + (size_t)(t + 2) * kstep; const char* b2 = last ? nB : cB + (size_t)(t + 2) * kstep;
;             const char* a3 = a2 + kstep; const char* b3 = b2 + kstep;
;             PG8_LDB(B0, 0, 0); PG8_LDB(B1, 0, 1); PG8_SCHED; PG8_LDA(At, 0, 0); PG8_STAGE(PG8_SA(1, 1), a1 + hstepA, voffA);
;             PG8_WAIT_V(8); PG8_WAIT_L(0); PG8_BAR; PG8_MMA(0, 0, At, B0); PG8_MMA(0, 1, At, B1); PG8_BAR; PG8_SCHED;
;             PG8_LDA(At, 0, 1); PG8_STAGE(PG8_SB(0, 0), b2, voffB); PG8_STAGE(PG8_SB(0, 1), b2 + hstepB, voffB); PG8_STAGE(PG8_SA(0, 0), a2, voffA);
;             PG8_WAIT_V(8); PG8_WAIT_L(0); PG8_BAR; PG8_MMA(1, 0, At, B0); PG8_MMA(1, 1, At, B1); PG8_BAR; PG8_SCHED;
.LBB0_118:
	ds_read_b128 v[128:131], v183
	ds_read_b128 v[132:135], v183 offset:1024
	ds_read_b128 v[136:139], v183 offset:2048
	ds_read_b128 v[140:143], v183 offset:3072
	ds_read_b128 v[144:147], v184
	ds_read_b128 v[148:151], v184 offset:1024
	ds_read_b128 v[164:167], v184 offset:2048
	ds_read_b128 v[168:171], v184 offset:3072
	s_add_u32 s4, s0, 0xfffc0080
	s_addc_u32 s5, s1, -1
	s_cmp_eq_u32 s39, 12
	s_cselect_b32 s27, s12, s5
	s_cselect_b32 s26, s13, s4
	s_cselect_b32 s5, s24, s37
	s_cselect_b32 s4, s25, s29
	v_lshl_add_u64 v[190:191], s[0:1], 0, v[158:159]
	s_add_i32 m0, s45, 0xc000
	ds_read_b128 v[172:175], v185
	ds_read_b128 v[176:179], v185 offset:1024
	ds_read_b128 v[194:197], v185 offset:2048
	ds_read_b128 v[198:201], v185 offset:3072
	ds_read_b128 v[202:205], v185 offset:4096
	ds_read_b128 v[206:209], v185 offset:5120
	ds_read_b128 v[210:213], v185 offset:6144
	ds_read_b128 v[214:217], v185 offset:7168
	global_load_lds_dwordx4 v[190:191], off
	v_lshl_add_u64 v[190:191], s[0:1], 0, v[160:161]
	s_add_i32 m0, s45, 0xe000
	s_nop 0
	global_load_lds_dwordx4 v[190:191], off
	s_waitcnt vmcnt(8)
	s_waitcnt lgkmcnt(0)
	s_barrier
	s_waitcnt lgkmcnt(0)
	v_mfma_f32_16x16x32_bf16 v[124:127], v[128:131], v[172:175], v[124:127]
	v_mfma_f32_16x16x32_bf16 v[120:123], v[136:139], v[172:175], v[120:123]
	v_mfma_f32_16x16x32_bf16 v[108:111], v[128:131], v[194:197], v[108:111]
	v_mfma_f32_16x16x32_bf16 v[104:107], v[136:139], v[194:197], v[104:107]
	v_mfma_f32_16x16x32_bf16 v[92:95], v[128:131], v[202:205], v[92:95]
	v_mfma_f32_16x16x32_bf16 v[88:91], v[136:139], v[202:205], v[88:91]
	v_mfma_f32_16x16x32_bf16 v[76:79], v[128:131], v[210:213], v[76:79]
	v_mfma_f32_16x16x32_bf16 v[72:75], v[136:139], v[210:213], v[72:75]
	v_mfma_f32_16x16x32_bf16 v[124:127], v[132:135], v[176:179], v[124:127]
	v_mfma_f32_16x16x32_bf16 v[120:123], v[140:143], v[176:179], v[120:123]
	v_mfma_f32_16x16x32_bf16 v[108:111], v[132:135], v[198:201], v[108:111]
	v_mfma_f32_16x16x32_bf16 v[104:107], v[140:143], v[198:201], v[104:107]
	v_mfma_f32_16x16x32_bf16 v[92:95], v[132:135], v[206:209], v[92:95]
	v_mfma_f32_16x16x32_bf16 v[88:91], v[140:143], v[206:209], v[88:91]
	v_mfma_f32_16x16x32_bf16 v[76:79], v[132:135], v[214:217], v[76:79]
	v_mfma_f32_16x16x32_bf16 v[72:75], v[140:143], v[214:217], v[72:75]
	v_mfma_f32_16x16x32_bf16 v[116:119], v[144:147], v[172:175], v[116:119]
	v_mfma_f32_16x16x32_bf16 v[112:115], v[164:167], v[172:175], v[112:115]
	v_mfma_f32_16x16x32_bf16 v[100:103], v[144:147], v[194:197], v[100:103]
	v_mfma_f32_16x16x32_bf16 v[96:99], v[164:167], v[194:197], v[96:99]
	v_mfma_f32_16x16x32_bf16 v[84:87], v[144:147], v[202:205], v[84:87]
	v_mfma_f32_16x16x32_bf16 v[80:83], v[164:167], v[202:205], v[80:83]
	v_mfma_f32_16x16x32_bf16 v[68:71], v[144:147], v[210:213], v[68:71]
	v_mfma_f32_16x16x32_bf16 v[64:67], v[164:167], v[210:213], v[64:67]
	v_mfma_f32_16x16x32_bf16 v[116:119], v[148:151], v[176:179], v[116:119]
	v_mfma_f32_16x16x32_bf16 v[112:115], v[168:171], v[176:179], v[112:115]
	v_mfma_f32_16x16x32_bf16 v[100:103], v[148:151], v[198:201], v[100:103]
	v_mfma_f32_16x16x32_bf16 v[96:99], v[168:171], v[198:201], v[96:99]
	v_mfma_f32_16x16x32_bf16 v[84:87], v[148:151], v[206:209], v[84:87]
	v_mfma_f32_16x16x32_bf16 v[80:83], v[168:171], v[206:209], v[80:83]
	v_mfma_f32_16x16x32_bf16 v[68:71], v[148:151], v[214:217], v[68:71]
	v_mfma_f32_16x16x32_bf16 v[64:67], v[168:171], v[214:217], v[64:67]
	s_barrier
	s_add_i32 s79, s10, s33
	v_lshl_add_u64 v[190:191], s[4:5], 0, v[152:153]
	s_mov_b32 m0, s79
	ds_read_b128 v[172:175], v185 offset:16384
	ds_read_b128 v[176:179], v185 offset:17408
	ds_read_b128 v[194:197], v185 offset:18432
	ds_read_b128 v[198:201], v185 offset:19456
	ds_read_b128 v[202:205], v185 offset:20480
	ds_read_b128 v[206:209], v185 offset:21504
	ds_read_b128 v[210:213], v185 offset:22528
	ds_read_b128 v[214:217], v185 offset:23552
	global_load_lds_dwordx4 v[190:191], off
	s_add_i32 m0, s79, 0x2000
	s_add_u32 s88, s4, 0x40000
	v_lshl_add_u64 v[218:219], s[4:5], 0, v[154:155]
	s_addc_u32 s89, s5, 0
	s_add_i32 s79, s11, s33
	global_load_lds_dwordx4 v[218:219], off
	v_lshl_add_u64 v[220:221], s[88:89], 0, v[152:153]
	s_mov_b32 m0, s79
	v_lshl_add_u64 v[222:223], s[26:27], 0, v[154:155]
	global_load_lds_dwordx4 v[220:221], off
	v_lshl_add_u64 v[220:221], s[88:89], 0, v[154:155]
	s_add_i32 m0, s79, 0x2000
	s_nop 0
	global_load_lds_dwordx4 v[220:221], off
	v_lshl_add_u64 v[220:221], s[26:27], 0, v[152:153]
	s_mov_b32 m0, s45
	s_nop 0
	global_load_lds_dwordx4 v[220:221], off
	s_mov_b32 m0, s77
	s_nop 0
	global_load_lds_dwordx4 v[222:223], off
	s_waitcnt vmcnt(8)
	s_waitcnt lgkmcnt(0)
	s_barrier
; #define PG8_STAGE(bufoff, gbase, voff) do { _Pragma("unroll") for (int _i = 0; _i < 2; ++_i) \
;         __builtin_amdgcn_global_load_lds((const unsigned*)((const char*)(gbase) + (voff)[_i]), (LAS unsigned*)(lds + (bufoff) + ldsw + _i * 8192), 16, 0, 0); } while (0)
; #define PG8_LDA(dst, b, h) do { _Pragma("unroll") for (int m = 0; m < 4; ++m) _Pragma("unroll") for (int k = 0; k < 2; ++k) dst[m][k] = *(const LAS bf16x8*)(lds + PG8_SA(b, h) + aoff + m * 2048 + k * 1024); } while (0)
; #define PG8_LDB(dst, b, h) do { _Pragma("unroll") for (int n = 0; n < 2; ++n) _Pragma("unroll") for (int k = 0; k < 2; ++k) dst[n][k] = *(const LAS bf16x8*)(lds + PG8_SB(b, h) + boff + n * 2048 + k * 1024); } while (0)
; #define PG8_MMA(ai, bj, At, Bt) do { __builtin_amdgcn_s_setprio(1); _Pragma("unroll") for (int m = 0; m < 4; ++m) _Pragma("unroll") for (int n = 0; n < 2; ++n) _Pragma("unroll") for (int k = 0; k < 2; ++k) \
;         acc[ai][bj][m][n] = __builtin_amdgcn_mfma_f32_16x16x32_bf16(Bt[n][k], At[m][k], acc[ai][bj][m][n], 0, 0, 0); __builtin_amdgcn_s_setprio(0); } while (0)
; #define PG8_WAIT_V(n) asm volatile("s_waitcnt vmcnt(" #n ")" ::: "memory")
; #define PG8_WAIT_L(n) asm volatile("s_waitcnt lgkmcnt(" #n ")" ::: "memory")
; #define PG8_BAR __builtin_amdgcn_s_barrier()
; #define PG8_SCHED __builtin_amdgcn_sched_barrier(0)
; template <class Epi, class Sched>
; __device__ __forceinline__ void gemm_phase(LAS unsigned char* lds, const Gemm g, const Sched& S, const Epi& E) {
;     ...
;             PG8_WAIT_V(8); PG8_WAIT_L(0); PG8_BAR; PG8_MMA(1, 0, At, B0); PG8_MMA(1, 1, At, B1); PG8_BAR; PG8_SCHED;
;             PG8_LDB(B0, 1, 0); PG8_LDB(B1, 1, 1); PG8_SCHED; PG8_LDA(At, 1, 0); PG8_STAGE(PG8_SA(0, 1), a2 + hstepA, voffA);
;             PG8_WAIT_V(8); PG8_WAIT_L(0); PG8_BAR; PG8_MMA(0, 0, At, B0); PG8_MMA(0, 1, At, B1); PG8_BAR; PG8_SCHED;
;             PG8_LDA(At, 1, 1); PG8_STAGE(PG8_SB(1, 0), b3, voffB); PG8_STAGE(PG8_SB(1, 1), b3 + hstepB, voffB); PG8_STAGE(PG8_SA(1, 0), a3, voffA);
;             PG8_WAIT_V(8); PG8_WAIT_L(0); PG8_BAR; PG8_MMA(1, 0, At, B0); PG8_MMA(1, 1, At, B1); PG8_BAR; PG8_SCHED;
	s_waitcnt lgkmcnt(0)
	v_mfma_f32_16x16x32_bf16 v[60:63], v[128:131], v[172:175], v[60:63]
	v_mfma_f32_16x16x32_bf16 v[56:59], v[136:139], v[172:175], v[56:59]
	v_mfma_f32_16x16x32_bf16 v[44:47], v[128:131], v[194:197], v[44:47]
	v_mfma_f32_16x16x32_bf16 v[40:43], v[136:139], v[194:197], v[40:43]
	v_mfma_f32_16x16x32_bf16 v[28:31], v[128:131], v[202:205], v[28:31]
	v_mfma_f32_16x16x32_bf16 v[24:27], v[136:139], v[202:205], v[24:27]
	v_mfma_f32_16x16x32_bf16 v[12:15], v[128:131], v[210:213], v[12:15]
	v_mfma_f32_16x16x32_bf16 v[8:11], v[136:139], v[210:213], v[8:11]
	v_mfma_f32_16x16x32_bf16 v[60:63], v[132:135], v[176:179], v[60:63]
	v_mfma_f32_16x16x32_bf16 v[56:59], v[140:143], v[176:179], v[56:59]
	v_mfma_f32_16x16x32_bf16 v[44:47], v[132:135], v[198:201], v[44:47]
	v_mfma_f32_16x16x32_bf16 v[40:43], v[140:143], v[198:201], v[40:43]
	v_mfma_f32_16x16x32_bf16 v[28:31], v[132:135], v[206:209], v[28:31]
	v_mfma_f32_16x16x32_bf16 v[24:27], v[140:143], v[206:209], v[24:27]
	v_mfma_f32_16x16x32_bf16 v[12:15], v[132:135], v[214:217], v[12:15]
	v_mfma_f32_16x16x32_bf16 v[8:11], v[140:143], v[214:217], v[8:11]
	v_mfma_f32_16x16x32_bf16 v[52:55], v[144:147], v[172:175], v[52:55]
	v_mfma_f32_16x16x32_bf16 v[48:51], v[164:167], v[172:175], v[48:51]
	v_mfma_f32_16x16x32_bf16 v[36:39], v[144:147], v[194:197], v[36:39]
	v_mfma_f32_16x16x32_bf16 v[32:35], v[164:167], v[194:197], v[32:35]
	v_mfma_f32_16x16x32_bf16 v[20:23], v[144:147], v[202:205], v[20:23]
	v_mfma_f32_16x16x32_bf16 v[16:19], v[164:167], v[202:205], v[16:19]
	v_mfma_f32_16x16x32_bf16 v[4:7], v[144:147], v[210:213], v[4:7]
	v_mfma_f32_16x16x32_bf16 v[0:3], v[164:167], v[210:213], v[0:3]
	v_mfma_f32_16x16x32_bf16 v[52:55], v[148:151], v[176:179], v[52:55]
	v_mfma_f32_16x16x32_bf16 v[48:51], v[168:171], v[176:179], v[48:51]
	v_mfma_f32_16x16x32_bf16 v[36:39], v[148:151], v[198:201], v[36:39]
	v_mfma_f32_16x16x32_bf16 v[32:35], v[168:171], v[198:201], v[32:35]
	v_mfma_f32_16x16x32_bf16 v[20:23], v[148:151], v[206:209], v[20:23]
	v_mfma_f32_16x16x32_bf16 v[16:19], v[168:171], v[206:209], v[16:19]
	v_mfma_f32_16x16x32_bf16 v[4:7], v[148:151], v[214:217], v[4:7]
	v_mfma_f32_16x16x32_bf16 v[0:3], v[168:171], v[214:217], v[0:3]
	s_barrier
	s_add_i32 s79, 0, 0x18000
	s_add_i32 s88, 0, 0x1c000
	v_add_u32_e32 v140, s79, v181
	v_add_u32_e32 v156, s88, v181
	ds_read_b128 v[128:131], v140
	ds_read_b128 v[132:135], v140 offset:1024
	ds_read_b128 v[136:139], v140 offset:2048
	ds_read_b128 v[140:143], v140 offset:3072
	ds_read_b128 v[144:147], v156
	ds_read_b128 v[148:151], v156 offset:1024
	ds_read_b128 v[164:167], v156 offset:2048
	ds_read_b128 v[168:171], v156 offset:3072
	s_add_u32 s26, s26, 0x40000
	s_addc_u32 s27, s27, 0
	s_mov_b32 m0, s82
	v_lshl_add_u64 v[224:225], s[26:27], 0, v[152:153]
	ds_read_b128 v[172:175], v185 offset:32768
	ds_read_b128 v[176:179], v185 offset:33792
	ds_read_b128 v[194:197], v185 offset:34816
	ds_read_b128 v[198:201], v185 offset:35840
	ds_read_b128 v[202:205], v185 offset:36864
	ds_read_b128 v[206:209], v185 offset:37888
	ds_read_b128 v[210:213], v185 offset:38912
	ds_read_b128 v[214:217], v185 offset:39936
	global_load_lds_dwordx4 v[224:225], off
	v_lshl_add_u64 v[224:225], s[26:27], 0, v[154:155]
	s_mov_b32 m0, s83
	s_nop 0
	global_load_lds_dwordx4 v[224:225], off
	s_waitcnt vmcnt(8)
	s_waitcnt lgkmcnt(0)
	s_barrier
	s_waitcnt lgkmcnt(0)
	v_mfma_f32_16x16x32_bf16 v[124:127], v[128:131], v[172:175], v[124:127]
	v_mfma_f32_16x16x32_bf16 v[120:123], v[136:139], v[172:175], v[120:123]
	v_mfma_f32_16x16x32_bf16 v[108:111], v[128:131], v[194:197], v[108:111]
	v_mfma_f32_16x16x32_bf16 v[104:107], v[136:139], v[194:197], v[104:107]
	v_mfma_f32_16x16x32_bf16 v[92:95], v[128:131], v[202:205], v[92:95]
	v_mfma_f32_16x16x32_bf16 v[88:91], v[136:139], v[202:205], v[88:91]
	v_mfma_f32_16x16x32_bf16 v[76:79], v[128:131], v[210:213], v[76:79]
	v_mfma_f32_16x16x32_bf16 v[72:75], v[136:139], v[210:213], v[72:75]
	v_mfma_f32_16x16x32_bf16 v[124:127], v[132:135], v[176:179], v[124:127]
	v_mfma_f32_16x16x32_bf16 v[120:123], v[140:143], v[176:179], v[120:123]
	v_mfma_f32_16x16x32_bf16 v[108:111], v[132:135], v[198:201], v[108:111]
	v_mfma_f32_16x16x32_bf16 v[104:107], v[140:143], v[198:201], v[104:107]
	v_mfma_f32_16x16x32_bf16 v[92:95], v[132:135], v[206:209], v[92:95]
	v_mfma_f32_16x16x32_bf16 v[88:91], v[140:143], v[206:209], v[88:91]
	v_mfma_f32_16x16x32_bf16 v[76:79], v[132:135], v[214:217], v[76:79]
	v_mfma_f32_16x16x32_bf16 v[72:75], v[140:143], v[214:217], v[72:75]
	v_mfma_f32_16x16x32_bf16 v[116:119], v[144:147], v[172:175], v[116:119]
	v_mfma_f32_16x16x32_bf16 v[112:115], v[164:167], v[172:175], v[112:115]
	v_mfma_f32_16x16x32_bf16 v[100:103], v[144:147], v[194:197], v[100:103]
	v_mfma_f32_16x16x32_bf16 v[96:99], v[164:167], v[194:197], v[96:99]
	v_mfma_f32_16x16x32_bf16 v[84:87], v[144:147], v[202:205], v[84:87]
	v_mfma_f32_16x16x32_bf16 v[80:83], v[164:167], v[202:205], v[80:83]
	v_mfma_f32_16x16x32_bf16 v[68:71], v[144:147], v[210:213], v[68:71]
	v_mfma_f32_16x16x32_bf16 v[64:67], v[164:167], v[210:213], v[64:67]
	v_mfma_f32_16x16x32_bf16 v[116:119], v[148:151], v[176:179], v[116:119]
	v_mfma_f32_16x16x32_bf16 v[112:115], v[168:171], v[176:179], v[112:115]
	v_mfma_f32_16x16x32_bf16 v[100:103], v[148:151], v[198:201], v[100:103]
	v_mfma_f32_16x16x32_bf16 v[96:99], v[168:171], v[198:201], v[96:99]
	v_mfma_f32_16x16x32_bf16 v[84:87], v[148:151], v[206:209], v[84:87]
	v_mfma_f32_16x16x32_bf16 v[80:83], v[168:171], v[206:209], v[80:83]
	v_mfma_f32_16x16x32_bf16 v[68:71], v[148:151], v[214:217], v[68:71]
	v_mfma_f32_16x16x32_bf16 v[64:67], v[168:171], v[214:217], v[64:67]
	s_barrier
; #define PG8_STAGE(bufoff, gbase, voff) do { _Pragma("unroll") for (int _i = 0; _i < 2; ++_i) \
;         __builtin_amdgcn_global_load_lds((const unsigned*)((const char*)(gbase) + (voff)[_i]), (LAS unsigned*)(lds + (bufoff) + ldsw + _i * 8192), 16, 0, 0); } while (0)
; #define PG8_LDA(dst, b, h) do { _Pragma("unroll") for (int m = 0; m < 4; ++m) _Pragma("unroll") for (int k = 0; k < 2; ++k) dst[m][k] = *(const LAS bf16x8*)(lds + PG8_SA(b, h) + aoff + m * 2048 + k * 1024); } while (0)
; #define PG8_MMA(ai, bj, At, Bt) do { __builtin_amdgcn_s_setprio(1); _Pragma("unroll") for (int m = 0; m < 4; ++m) _Pragma("unroll") for (int n = 0; n < 2; ++n) _Pragma("unroll") for (int k = 0; k < 2; ++k) \
;         acc[ai][bj][m][n] = __builtin_amdgcn_mfma_f32_16x16x32_bf16(Bt[n][k], At[m][k], acc[ai][bj][m][n], 0, 0, 0); __builtin_amdgcn_s_setprio(0); } while (0)
; #define PG8_WAIT_V(n) asm volatile("s_waitcnt vmcnt(" #n ")" ::: "memory")
; #define PG8_WAIT_L(n) asm volatile("s_waitcnt lgkmcnt(" #n ")" ::: "memory")
; #define PG8_BAR __builtin_amdgcn_s_barrier()
; #define PG8_SCHED __builtin_amdgcn_sched_barrier(0)
; template <class Epi, class Sched>
; __device__ __forceinline__ void gemm_phase(LAS unsigned char* lds, const Gemm g, const Sched& S, const Epi& E) {
;     ...
;         for (int t = 0; t < nt; t += 2) {
;     ...
;             PG8_LDA(At, 1, 1); PG8_STAGE(PG8_SB(1, 0), b3, voffB); PG8_STAGE(PG8_SB(1, 1), b3 + hstepB, voffB); PG8_STAGE(PG8_SA(1, 0), a3, voffA);
;             PG8_WAIT_V(8); PG8_WAIT_L(0); PG8_BAR; PG8_MMA(1, 0, At, B0); PG8_MMA(1, 1, At, B1); PG8_BAR; PG8_SCHED;
	s_add_i32 s26, s79, s33
	v_lshl_add_u64 v[190:191], v[190:191], 0, s[20:21]
	s_mov_b32 m0, s26
	ds_read_b128 v[172:175], v185 offset:49152
	ds_read_b128 v[176:179], v185 offset:50176
	ds_read_b128 v[194:197], v185 offset:51200
	ds_read_b128 v[198:201], v185 offset:52224
	ds_read_b128 v[202:205], v185 offset:53248
	ds_read_b128 v[206:209], v185 offset:54272
	ds_read_b128 v[210:213], v185 offset:55296
	ds_read_b128 v[214:217], v185 offset:56320
	global_load_lds_dwordx4 v[190:191], off
	s_add_i32 m0, s26, 0x2000
	s_add_u32 s4, s4, 0x40080
	v_lshl_add_u64 v[190:191], v[218:219], 0, s[20:21]
	s_addc_u32 s5, s5, 0
	s_add_i32 s26, s88, s33
	global_load_lds_dwordx4 v[190:191], off
	v_lshl_add_u64 v[190:191], s[4:5], 0, v[152:153]
	s_mov_b32 m0, s26
	s_nop 0
	global_load_lds_dwordx4 v[190:191], off
	v_lshl_add_u64 v[190:191], s[4:5], 0, v[154:155]
	s_add_i32 m0, s26, 0x2000
	s_nop 0
	global_load_lds_dwordx4 v[190:191], off
	v_lshl_add_u64 v[190:191], v[220:221], 0, s[20:21]
	s_mov_b32 m0, s85
	s_nop 0
	global_load_lds_dwordx4 v[190:191], off
	v_lshl_add_u64 v[190:191], v[222:223], 0, s[20:21]
	s_mov_b32 m0, s44
	s_nop 0
	global_load_lds_dwordx4 v[190:191], off
	s_waitcnt vmcnt(8)
	s_waitcnt lgkmcnt(0)
	s_barrier
	s_waitcnt lgkmcnt(0)
	v_mfma_f32_16x16x32_bf16 v[60:63], v[128:131], v[172:175], v[60:63]
	v_mfma_f32_16x16x32_bf16 v[56:59], v[136:139], v[172:175], v[56:59]
	v_mfma_f32_16x16x32_bf16 v[44:47], v[128:131], v[194:197], v[44:47]
	v_mfma_f32_16x16x32_bf16 v[40:43], v[136:139], v[194:197], v[40:43]
	v_mfma_f32_16x16x32_bf16 v[28:31], v[128:131], v[202:205], v[28:31]
	v_mfma_f32_16x16x32_bf16 v[24:27], v[136:139], v[202:205], v[24:27]
	v_mfma_f32_16x16x32_bf16 v[12:15], v[128:131], v[210:213], v[12:15]
	v_mfma_f32_16x16x32_bf16 v[8:11], v[136:139], v[210:213], v[8:11]
	v_mfma_f32_16x16x32_bf16 v[60:63], v[132:135], v[176:179], v[60:63]
	v_mfma_f32_16x16x32_bf16 v[56:59], v[140:143], v[176:179], v[56:59]
	v_mfma_f32_16x16x32_bf16 v[44:47], v[132:135], v[198:201], v[44:47]
	v_mfma_f32_16x16x32_bf16 v[40:43], v[140:143], v[198:201], v[40:43]
	v_mfma_f32_16x16x32_bf16 v[28:31], v[132:135], v[206:209], v[28:31]
	v_mfma_f32_16x16x32_bf16 v[24:27], v[140:143], v[206:209], v[24:27]
	v_mfma_f32_16x16x32_bf16 v[12:15], v[132:135], v[214:217], v[12:15]
	v_mfma_f32_16x16x32_bf16 v[8:11], v[140:143], v[214:217], v[8:11]
	v_mfma_f32_16x16x32_bf16 v[52:55], v[144:147], v[172:175], v[52:55]
	v_mfma_f32_16x16x32_bf16 v[48:51], v[164:167], v[172:175], v[48:51]
	v_mfma_f32_16x16x32_bf16 v[36:39], v[144:147], v[194:197], v[36:39]
	v_mfma_f32_16x16x32_bf16 v[32:35], v[164:167], v[194:197], v[32:35]
	v_mfma_f32_16x16x32_bf16 v[20:23], v[144:147], v[202:205], v[20:23]
	v_mfma_f32_16x16x32_bf16 v[16:19], v[164:167], v[202:205], v[16:19]
	v_mfma_f32_16x16x32_bf16 v[4:7], v[144:147], v[210:213], v[4:7]
	v_mfma_f32_16x16x32_bf16 v[0:3], v[164:167], v[210:213], v[0:3]
	v_mfma_f32_16x16x32_bf16 v[52:55], v[148:151], v[176:179], v[52:55]
	v_mfma_f32_16x16x32_bf16 v[48:51], v[168:171], v[176:179], v[48:51]
	v_mfma_f32_16x16x32_bf16 v[36:39], v[148:151], v[198:201], v[36:39]
	v_mfma_f32_16x16x32_bf16 v[32:35], v[168:171], v[198:201], v[32:35]
	v_mfma_f32_16x16x32_bf16 v[20:23], v[148:151], v[206:209], v[20:23]
	v_mfma_f32_16x16x32_bf16 v[16:19], v[168:171], v[206:209], v[16:19]
	v_mfma_f32_16x16x32_bf16 v[4:7], v[148:151], v[214:217], v[4:7]
	v_mfma_f32_16x16x32_bf16 v[0:3], v[168:171], v[214:217], v[0:3]
	s_barrier
	s_add_i32 s39, s39, 2
	s_add_u32 s0, s0, 0x100
	s_addc_u32 s1, s1, 0
	s_add_u32 s29, s29, 0x100
	s_addc_u32 s37, s37, 0
	s_cmp_gt_u32 s39, 13
	s_cbranch_scc0 .LBB0_118
	s_and_b64 vcc, exec, s[22:23]
	s_cbranch_vccz .LBB0_121
	s_barrier

; #define SEAM(k) do { if (COOP && IN(k) && IN((k) + 1)) { xcd_barrier(bar); } } while (0)
; __device__ __forceinline__ void xcd_barrier(const XcdBarrier& b) {
;     asm volatile("s_waitcnt vmcnt(0)" ::: "memory");
;     __syncthreads();
;     if (threadIdx.x == 0) {
;         unsigned* bar = b.bar;
;         __builtin_amdgcn_s_waitcnt(0);
;         unsigned nloc = b.st[0], nx = b.st[1];
;         if (nloc == 0u) { xcd_barrier_complete(bar, b.x, nloc, nx); b.st[0] = nloc; b.st[1] = nx; }
; template <bool COOP>
; __global__ void __launch_bounds__(512, 2) mega(Args a) {
;     ...
;     SEAM(1);
.LBB0_242:
	s_setprio 0
	s_cmp_gt_i32 s83, 2
	s_cselect_b64 s[0:1], -1, 0
	s_and_b64 s[4:5], s[14:15], s[0:1]
	s_andn2_b64 vcc, exec, s[4:5]
	s_cbranch_vccnz .LBB0_296
	s_waitcnt vmcnt(0)
	s_waitcnt vmcnt(0) lgkmcnt(0)
	s_barrier
	s_and_saveexec_b64 s[4:5], s[96:97]
	s_cbranch_execz .LBB0_295
	s_add_i32 s6, 0, 0x22000
	v_mov_b32_e32 v0, s6
	s_waitcnt vmcnt(0) expcnt(0) lgkmcnt(0)
	ds_read_b32 v2, v0
	s_add_i32 s6, 0, 0x22004
	v_mov_b32_e32 v0, s6
	ds_read_b32 v0, v0
	s_waitcnt lgkmcnt(1)
	v_cmp_ne_u32_e32 vcc, 0, v2
	s_cbranch_vccnz .LBB0_259
	v_readlane_b32 s10, v255, 0
	v_readlane_b32 s11, v255, 1
	s_load_dwordx2 s[6:7], s[10:11], 0x4
	s_add_u32 s10, s62, 0x1de00200
	s_addc_u32 s11, s63, 0
	s_add_u32 s12, s62, 0x1de00400
	s_addc_u32 s13, s63, 0
	s_add_u32 s14, s62, 0x1de00500
	s_addc_u32 s15, s63, 0
	s_add_u32 s16, s62, 0x1de00600
	s_addc_u32 s17, s63, 0
	s_add_u32 s18, s62, 0x1de00700
	s_addc_u32 s19, s63, 0
	s_add_u32 s20, s62, 0x1de00800
	s_addc_u32 s21, s63, 0
	s_add_u32 s22, s62, 0x1de00900
	s_addc_u32 s23, s63, 0
	s_add_u32 s24, s62, 0x1de00a00
	s_addc_u32 s25, s63, 0
	s_add_u32 s26, s62, 0x1de00b00
	s_addc_u32 s27, s63, 0
	s_add_u32 s28, s62, 0x1de00c00
	s_addc_u32 s29, s63, 0
	s_add_u32 s30, s62, 0x1de00d00
	s_addc_u32 s31, s63, 0
	s_add_u32 s34, s62, 0x1de00e00
	s_addc_u32 s35, s63, 0
	s_add_u32 s36, s62, 0x1de00f00
	s_addc_u32 s37, s63, 0
	s_add_u32 s38, s62, 0x1de01000
	s_addc_u32 s39, s63, 0
	s_add_u32 s40, s62, 0x1de01100
	s_addc_u32 s41, s63, 0
	s_add_u32 s42, s62, 0x1de01200
	s_addc_u32 s43, s63, 0
	s_waitcnt lgkmcnt(0)
	s_mul_i32 s33, s6, s3
	s_add_u32 s58, s62, 0x1de01300
	s_mul_i32 s33, s33, s7
	s_addc_u32 s59, s63, 0
	s_mov_b32 s44, 1
	v_mov_b32_e32 v16, 0
	s_branch .LBB0_247
